# NSA item loop: end-of-item workgroup barrier dropped (implied by the next item's two barriers)
# baseline (speedup 1.0000x reference)
.LBB0_778:
	v_lshlrev_b32_e32 v64, 16, v165
	v_mul_f32_e32 v64, 0xbfb8aa3b, v64
	v_exp_f32_e32 v64, v64
	v_and_b32_e32 v65, 0xffff0000, v166
	v_mul_f32_e32 v65, 0xbfb8aa3b, v65
	v_exp_f32_e32 v65, v65
	v_add_f32_e32 v64, 1.0, v64
	v_div_scale_f32 v66, s[0:1], v64, v64, 1.0
	v_rcp_f32_e32 v67, v66
	v_div_scale_f32 v70, vcc, 1.0, v64, 1.0
	s_add_i32 s90, s90, 1
	v_fma_f32 v68, -v66, v67, 1.0
	v_fmac_f32_e32 v67, v68, v67
	global_load_dwordx2 v[68:69], v[160:161], off
	v_mul_f32_e32 v71, v70, v67
	v_fma_f32 v72, -v66, v71, v70
	v_fmac_f32_e32 v71, v72, v67
	v_fma_f32 v66, -v66, v71, v70
	v_add_f32_e32 v70, 1.0, v65
	v_div_scale_f32 v72, s[0:1], v70, v70, 1.0
	v_rcp_f32_e32 v73, v72
	v_div_fmas_f32 v65, v66, v67, v71
	v_div_fixup_f32 v74, v65, v64, 1.0
	ds_bpermute_b32 v65, v177, v163
	v_fma_f32 v64, -v72, v73, 1.0
	v_fmac_f32_e32 v73, v64, v73
	ds_bpermute_b32 v64, v177, v162
	v_div_scale_f32 v66, vcc, 1.0, v70, 1.0
	v_mul_f32_e32 v71, v66, v73
	v_fma_f32 v67, -v72, v71, v66
	s_waitcnt lgkmcnt(0)
	v_pk_add_f32 v[64:65], v[162:163], v[64:65]
	v_fmac_f32_e32 v71, v67, v73
	v_div_scale_f32 v75, s[0:1], v64, v64, 1.0
	v_rcp_f32_e32 v76, v75
	v_fma_f32 v72, -v72, v71, v66
	v_div_fmas_f32 v71, v72, v73, v71
	v_div_fixup_f32 v73, v71, v70, 1.0
	v_fma_f32 v70, -v75, v76, 1.0
	v_fmac_f32_e32 v76, v70, v76
	v_div_scale_f32 v70, vcc, 1.0, v64, 1.0
	v_mul_f32_e32 v71, v70, v76
	v_fma_f32 v72, -v75, v71, v70
	v_fmac_f32_e32 v71, v72, v76
	v_fma_f32 v70, -v75, v71, v70
	v_div_scale_f32 v75, s[0:1], v65, v65, 1.0
	v_div_fmas_f32 v70, v70, v76, v71
	v_rcp_f32_e32 v76, v75
	v_div_fixup_f32 v70, v70, v64, 1.0
	v_cmp_lt_f32_e32 vcc, 0, v64
	global_load_dwordx2 v[66:67], v[160:161], off offset:64
	s_cmp_eq_u32 s90, 3
	v_cndmask_b32_e32 v64, 0, v70, vcc
	v_mul_f32_e32 v72, v74, v64
	v_fma_f32 v64, -v75, v76, 1.0
	v_fmac_f32_e32 v76, v64, v76
	v_div_scale_f32 v64, vcc, 1.0, v65, 1.0
	v_mul_f32_e32 v74, v64, v76
	v_fma_f32 v77, -v75, v74, v64
	v_fmac_f32_e32 v74, v77, v76
	v_fma_f32 v64, -v75, v74, v64
	v_div_fmas_f32 v64, v64, v76, v74
	global_load_dwordx2 v[74:75], v[160:161], off offset:80
	global_load_dwordx2 v[70:71], v[160:161], off offset:16
	v_div_fixup_f32 v64, v64, v65, 1.0
	v_cmp_lt_f32_e32 vcc, 0, v65
	v_pk_mul_f32 v[76:77], v[36:37], v[72:73] op_sel_hi:[1,0]
	v_pk_mul_f32 v[78:79], v[34:35], v[72:73] op_sel_hi:[1,0]
	v_cndmask_b32_e32 v64, 0, v64, vcc
	v_pk_mul_f32 v[80:81], v[32:33], v[72:73] op_sel_hi:[1,0]
	v_pk_mul_f32 v[34:35], v[60:61], v[72:73] op_sel_hi:[1,0]
	v_pk_mul_f32 v[36:37], v[58:59], v[72:73] op_sel_hi:[1,0]
	global_load_dwordx2 v[58:59], v[160:161], off offset:32
	global_load_dwordx2 v[60:61], v[160:161], off offset:48
	v_mul_f32_e32 v64, v73, v64
	v_pk_mul_f32 v[46:47], v[46:47], v[72:73] op_sel_hi:[1,0]
	v_pk_mul_f32 v[44:45], v[44:45], v[72:73] op_sel_hi:[1,0]
	v_pk_mul_f32 v[42:43], v[42:43], v[72:73] op_sel_hi:[1,0]
	v_pk_mul_f32 v[40:41], v[40:41], v[72:73] op_sel_hi:[1,0]
	v_pk_mul_f32 v[38:39], v[38:39], v[72:73] op_sel_hi:[1,0]
	v_pk_mul_f32 v[32:33], v[62:63], v[72:73] op_sel_hi:[1,0]
	v_pk_mul_f32 v[56:57], v[56:57], v[72:73] op_sel_hi:[1,0]
	v_pk_mul_f32 v[52:53], v[52:53], v[72:73] op_sel_hi:[1,0]
	v_pk_mul_f32 v[54:55], v[54:55], v[72:73] op_sel_hi:[1,0]
	v_pk_mul_f32 v[48:49], v[48:49], v[72:73] op_sel_hi:[1,0]
	v_pk_mul_f32 v[50:51], v[50:51], v[72:73] op_sel_hi:[1,0]
	v_pk_mov_b32 v[72:73], v[80:81], v[78:79] op_sel:[1,0]
	v_mov_b32_e32 v81, v79
	v_lshl_add_u64 v[206:207], v[206:207], 0, s[66:67]
	s_waitcnt vmcnt(5)
	v_and_b32_e32 v62, 0xffff0000, v68
	v_lshlrev_b32_e32 v63, 16, v69
	v_lshlrev_b32_e32 v68, 16, v68
	v_and_b32_e32 v69, 0xffff0000, v69
	v_pk_add_f32 v[62:63], v[72:73], v[62:63]
	v_pk_add_f32 v[68:69], v[80:81], v[68:69]
	v_and_b32_sdwa v72, v62, v232 dst_sel:DWORD dst_unused:UNUSED_PAD src0_sel:WORD_1 src1_sel:DWORD
	v_and_b32_sdwa v65, v63, v232 dst_sel:DWORD dst_unused:UNUSED_PAD src0_sel:WORD_1 src1_sel:DWORD
	v_add3_u32 v62, v62, v72, s81
	v_and_b32_sdwa v72, v68, v232 dst_sel:DWORD dst_unused:UNUSED_PAD src0_sel:WORD_1 src1_sel:DWORD
	v_add3_u32 v63, v63, v65, s81
	v_and_b32_e32 v62, 0xffff0000, v62
	v_and_b32_sdwa v65, v69, v232 dst_sel:DWORD dst_unused:UNUSED_PAD src0_sel:WORD_1 src1_sel:DWORD
	v_add3_u32 v68, v68, v72, s81
	v_add3_u32 v65, v69, v65, s81
	v_or_b32_sdwa v62, v68, v62 dst_sel:DWORD dst_unused:UNUSED_PAD src0_sel:WORD_1 src1_sel:DWORD
	global_load_dwordx2 v[68:69], v[160:161], off offset:96
	global_load_dwordx2 v[72:73], v[160:161], off offset:112
	v_mov_b32_e32 v81, v50
	v_mov_b32_e32 v50, v49
	v_and_b32_e32 v65, 0xffff0000, v65
	v_mov_b32_e32 v80, v48
	v_or_b32_sdwa v63, v65, v63 dst_sel:DWORD dst_unused:UNUSED_PAD src0_sel:DWORD src1_sel:WORD_1
	s_waitcnt vmcnt(6)
	v_lshlrev_b32_e32 v79, 16, v67
	v_lshlrev_b32_e32 v78, 16, v66
	v_and_b32_e32 v67, 0xffff0000, v67
	v_and_b32_e32 v66, 0xffff0000, v66
	v_pk_add_f32 v[48:49], v[50:51], v[66:67]
	v_pk_add_f32 v[78:79], v[80:81], v[78:79]
	v_and_b32_sdwa v65, v49, v232 dst_sel:DWORD dst_unused:UNUSED_PAD src0_sel:WORD_1 src1_sel:DWORD
	v_and_b32_sdwa v66, v48, v232 dst_sel:DWORD dst_unused:UNUSED_PAD src0_sel:WORD_1 src1_sel:DWORD
	v_and_b32_sdwa v50, v79, v232 dst_sel:DWORD dst_unused:UNUSED_PAD src0_sel:WORD_1 src1_sel:DWORD
	v_and_b32_sdwa v51, v78, v232 dst_sel:DWORD dst_unused:UNUSED_PAD src0_sel:WORD_1 src1_sel:DWORD
	v_add3_u32 v49, v49, v65, s81
	v_add3_u32 v48, v48, v66, s81
	v_add3_u32 v51, v78, v51, s81
	v_add3_u32 v50, v79, v50, s81
	v_and_b32_e32 v49, 0xffff0000, v49
	v_and_b32_e32 v48, 0xffff0000, v48
	v_or_b32_sdwa v49, v49, v50 dst_sel:DWORD dst_unused:UNUSED_PAD src0_sel:DWORD src1_sel:WORD_1
	v_or_b32_sdwa v48, v48, v51 dst_sel:DWORD dst_unused:UNUSED_PAD src0_sel:DWORD src1_sel:WORD_1
	global_store_dwordx2 v[160:161], v[62:63], off
	global_store_dwordx2 v[160:161], v[48:49], off offset:64
	s_waitcnt vmcnt(6)
	v_and_b32_e32 v48, 0xffff0000, v70
	v_lshlrev_b32_e32 v49, 16, v71
	v_pk_mov_b32 v[62:63], v[76:77], v[38:39] op_sel:[1,0]
	v_lshlrev_b32_e32 v50, 16, v70
	v_and_b32_e32 v51, 0xffff0000, v71
	v_pk_add_f32 v[48:49], v[62:63], v[48:49]
	v_mov_b32_e32 v77, v39
	v_pk_add_f32 v[38:39], v[76:77], v[50:51]
	v_and_b32_sdwa v50, v49, v232 dst_sel:DWORD dst_unused:UNUSED_PAD src0_sel:WORD_1 src1_sel:DWORD
	v_and_b32_sdwa v51, v48, v232 dst_sel:DWORD dst_unused:UNUSED_PAD src0_sel:WORD_1 src1_sel:DWORD
	v_add3_u32 v49, v49, v50, s81
	v_and_b32_sdwa v50, v39, v232 dst_sel:DWORD dst_unused:UNUSED_PAD src0_sel:WORD_1 src1_sel:DWORD
	v_add3_u32 v48, v48, v51, s81
	v_and_b32_sdwa v51, v38, v232 dst_sel:DWORD dst_unused:UNUSED_PAD src0_sel:WORD_1 src1_sel:DWORD
	v_add3_u32 v39, v39, v50, s81
	v_and_b32_e32 v48, 0xffff0000, v48
	v_add3_u32 v38, v38, v51, s81
	v_and_b32_e32 v39, 0xffff0000, v39
	v_or_b32_sdwa v39, v39, v49 dst_sel:DWORD dst_unused:UNUSED_PAD src0_sel:DWORD src1_sel:WORD_1
	v_or_b32_sdwa v38, v38, v48 dst_sel:DWORD dst_unused:UNUSED_PAD src0_sel:WORD_1 src1_sel:DWORD
	v_lshlrev_b32_e32 v49, 16, v75
	v_lshlrev_b32_e32 v48, 16, v74
	v_mov_b32_e32 v62, v52
	v_mov_b32_e32 v63, v54
	v_and_b32_e32 v51, 0xffff0000, v75
	v_and_b32_e32 v50, 0xffff0000, v74
	v_pk_add_f32 v[48:49], v[62:63], v[48:49]
	v_mov_b32_e32 v54, v53
	v_pk_add_f32 v[50:51], v[54:55], v[50:51]
	v_and_b32_sdwa v52, v49, v232 dst_sel:DWORD dst_unused:UNUSED_PAD src0_sel:WORD_1 src1_sel:DWORD
	v_and_b32_sdwa v53, v48, v232 dst_sel:DWORD dst_unused:UNUSED_PAD src0_sel:WORD_1 src1_sel:DWORD
	v_add3_u32 v48, v48, v53, s81
	v_add3_u32 v49, v49, v52, s81
	v_and_b32_sdwa v52, v51, v232 dst_sel:DWORD dst_unused:UNUSED_PAD src0_sel:WORD_1 src1_sel:DWORD
	v_and_b32_sdwa v53, v50, v232 dst_sel:DWORD dst_unused:UNUSED_PAD src0_sel:WORD_1 src1_sel:DWORD
	v_add3_u32 v51, v51, v52, s81
	v_add3_u32 v50, v50, v53, s81
	v_and_b32_e32 v51, 0xffff0000, v51
	v_and_b32_e32 v50, 0xffff0000, v50
	v_or_b32_sdwa v49, v51, v49 dst_sel:DWORD dst_unused:UNUSED_PAD src0_sel:DWORD src1_sel:WORD_1
	v_or_b32_sdwa v48, v50, v48 dst_sel:DWORD dst_unused:UNUSED_PAD src0_sel:DWORD src1_sel:WORD_1
	global_store_dwordx2 v[160:161], v[38:39], off offset:16
	global_store_dwordx2 v[160:161], v[48:49], off offset:80
	s_waitcnt vmcnt(7)
	v_and_b32_e32 v38, 0xffff0000, v58
	v_lshlrev_b32_e32 v39, 16, v59
	v_pk_mov_b32 v[50:51], v[40:41], v[42:43] op_sel:[1,0]
	v_lshlrev_b32_e32 v48, 16, v58
	v_and_b32_e32 v49, 0xffff0000, v59
	v_pk_add_f32 v[38:39], v[50:51], v[38:39]
	v_mov_b32_e32 v41, v43
	v_pk_add_f32 v[40:41], v[40:41], v[48:49]
	v_and_b32_sdwa v42, v39, v232 dst_sel:DWORD dst_unused:UNUSED_PAD src0_sel:WORD_1 src1_sel:DWORD
	v_and_b32_sdwa v43, v38, v232 dst_sel:DWORD dst_unused:UNUSED_PAD src0_sel:WORD_1 src1_sel:DWORD
	v_add3_u32 v39, v39, v42, s81
	v_and_b32_sdwa v42, v41, v232 dst_sel:DWORD dst_unused:UNUSED_PAD src0_sel:WORD_1 src1_sel:DWORD
	v_add3_u32 v38, v38, v43, s81
	v_and_b32_sdwa v43, v40, v232 dst_sel:DWORD dst_unused:UNUSED_PAD src0_sel:WORD_1 src1_sel:DWORD
	v_add3_u32 v41, v41, v42, s81
	v_and_b32_e32 v38, 0xffff0000, v38
	v_add3_u32 v40, v40, v43, s81
	v_and_b32_e32 v41, 0xffff0000, v41
	v_or_b32_sdwa v41, v41, v39 dst_sel:DWORD dst_unused:UNUSED_PAD src0_sel:DWORD src1_sel:WORD_1
	v_or_b32_sdwa v40, v40, v38 dst_sel:DWORD dst_unused:UNUSED_PAD src0_sel:WORD_1 src1_sel:DWORD
	s_waitcnt vmcnt(5)
	v_lshlrev_b32_e32 v39, 16, v69
	v_lshlrev_b32_e32 v38, 16, v68
	v_mov_b32_e32 v48, v56
	v_mov_b32_e32 v49, v36
	v_pk_add_f32 v[48:49], v[48:49], v[38:39]
	global_load_dwordx2 v[38:39], v[160:161], off offset:128
	v_and_b32_e32 v43, 0xffff0000, v69
	v_and_b32_e32 v42, 0xffff0000, v68
	v_mov_b32_e32 v36, v57
	v_pk_add_f32 v[36:37], v[36:37], v[42:43]
	v_and_b32_sdwa v42, v49, v232 dst_sel:DWORD dst_unused:UNUSED_PAD src0_sel:WORD_1 src1_sel:DWORD
	v_and_b32_sdwa v43, v48, v232 dst_sel:DWORD dst_unused:UNUSED_PAD src0_sel:WORD_1 src1_sel:DWORD
	v_add3_u32 v43, v48, v43, s81
	v_add3_u32 v42, v49, v42, s81
	v_and_b32_sdwa v48, v37, v232 dst_sel:DWORD dst_unused:UNUSED_PAD src0_sel:WORD_1 src1_sel:DWORD
	v_and_b32_sdwa v49, v36, v232 dst_sel:DWORD dst_unused:UNUSED_PAD src0_sel:WORD_1 src1_sel:DWORD
	v_add3_u32 v37, v37, v48, s81
	v_add3_u32 v36, v36, v49, s81
	v_and_b32_e32 v37, 0xffff0000, v37
	v_and_b32_e32 v36, 0xffff0000, v36
	v_or_b32_sdwa v37, v37, v42 dst_sel:DWORD dst_unused:UNUSED_PAD src0_sel:DWORD src1_sel:WORD_1
	v_or_b32_sdwa v36, v36, v43 dst_sel:DWORD dst_unused:UNUSED_PAD src0_sel:DWORD src1_sel:WORD_1
	global_store_dwordx2 v[160:161], v[40:41], off offset:32
	global_store_dwordx2 v[160:161], v[36:37], off offset:96
	v_and_b32_e32 v36, 0xffff0000, v60
	v_lshlrev_b32_e32 v37, 16, v61
	v_pk_mov_b32 v[42:43], v[44:45], v[46:47] op_sel:[1,0]
	v_lshlrev_b32_e32 v40, 16, v60
	v_and_b32_e32 v41, 0xffff0000, v61
	v_pk_add_f32 v[42:43], v[42:43], v[36:37]
	global_load_dwordx2 v[36:37], v[160:161], off offset:192
	v_mov_b32_e32 v45, v47
	v_pk_add_f32 v[40:41], v[44:45], v[40:41]
	v_and_b32_sdwa v44, v43, v232 dst_sel:DWORD dst_unused:UNUSED_PAD src0_sel:WORD_1 src1_sel:DWORD
	v_and_b32_sdwa v45, v42, v232 dst_sel:DWORD dst_unused:UNUSED_PAD src0_sel:WORD_1 src1_sel:DWORD
	v_add3_u32 v43, v43, v44, s81
	v_and_b32_sdwa v44, v41, v232 dst_sel:DWORD dst_unused:UNUSED_PAD src0_sel:WORD_1 src1_sel:DWORD
	v_add3_u32 v42, v42, v45, s81
	v_and_b32_sdwa v45, v40, v232 dst_sel:DWORD dst_unused:UNUSED_PAD src0_sel:WORD_1 src1_sel:DWORD
	v_add3_u32 v41, v41, v44, s81
	v_and_b32_e32 v42, 0xffff0000, v42
	v_add3_u32 v40, v40, v45, s81
	v_and_b32_e32 v41, 0xffff0000, v41
	v_or_b32_sdwa v41, v41, v43 dst_sel:DWORD dst_unused:UNUSED_PAD src0_sel:DWORD src1_sel:WORD_1
	v_or_b32_sdwa v40, v40, v42 dst_sel:DWORD dst_unused:UNUSED_PAD src0_sel:WORD_1 src1_sel:DWORD
	s_waitcnt vmcnt(8)
	v_lshlrev_b32_e32 v43, 16, v73
	v_lshlrev_b32_e32 v42, 16, v72
	v_mov_b32_e32 v46, v34
	v_mov_b32_e32 v47, v32
	v_and_b32_e32 v45, 0xffff0000, v73
	v_and_b32_e32 v44, 0xffff0000, v72
	v_pk_add_f32 v[42:43], v[46:47], v[42:43]
	v_mov_b32_e32 v32, v35
	global_load_dwordx2 v[34:35], v[160:161], off offset:144
	v_pk_add_f32 v[32:33], v[32:33], v[44:45]
	v_and_b32_sdwa v44, v43, v232 dst_sel:DWORD dst_unused:UNUSED_PAD src0_sel:WORD_1 src1_sel:DWORD
	v_and_b32_sdwa v45, v42, v232 dst_sel:DWORD dst_unused:UNUSED_PAD src0_sel:WORD_1 src1_sel:DWORD
	v_add3_u32 v42, v42, v45, s81
	v_add3_u32 v43, v43, v44, s81
	v_and_b32_sdwa v44, v33, v232 dst_sel:DWORD dst_unused:UNUSED_PAD src0_sel:WORD_1 src1_sel:DWORD
	v_and_b32_sdwa v45, v32, v232 dst_sel:DWORD dst_unused:UNUSED_PAD src0_sel:WORD_1 src1_sel:DWORD
	v_add3_u32 v33, v33, v44, s81
	v_add3_u32 v32, v32, v45, s81
	v_and_b32_e32 v33, 0xffff0000, v33
	v_and_b32_e32 v32, 0xffff0000, v32
	v_or_b32_sdwa v33, v33, v43 dst_sel:DWORD dst_unused:UNUSED_PAD src0_sel:DWORD src1_sel:WORD_1
	v_or_b32_sdwa v32, v32, v42 dst_sel:DWORD dst_unused:UNUSED_PAD src0_sel:DWORD src1_sel:WORD_1
	global_store_dwordx2 v[160:161], v[40:41], off offset:48
	global_store_dwordx2 v[160:161], v[32:33], off offset:112
	global_load_dwordx2 v[32:33], v[160:161], off offset:208
	v_pk_mul_f32 v[18:19], v[18:19], v[64:65] op_sel_hi:[1,0]
	v_pk_mul_f32 v[40:41], v[16:17], v[64:65] op_sel_hi:[1,0]
	v_pk_mul_f32 v[16:17], v[12:13], v[64:65] op_sel_hi:[1,0]
	v_pk_mul_f32 v[12:13], v[14:15], v[64:65] op_sel_hi:[1,0]
	global_load_dwordx2 v[14:15], v[160:161], off offset:160
	global_load_dwordx2 v[42:43], v[160:161], off offset:176
	v_pk_mov_b32 v[46:47], v[40:41], v[18:19] op_sel:[1,0]
	v_mov_b32_e32 v41, v19
	v_pk_mul_f32 v[0:1], v[0:1], v[64:65] op_sel_hi:[1,0]
	v_pk_mul_f32 v[2:3], v[2:3], v[64:65] op_sel_hi:[1,0]
	v_pk_mul_f32 v[22:23], v[22:23], v[64:65] op_sel_hi:[1,0]
	v_pk_mul_f32 v[20:21], v[20:21], v[64:65] op_sel_hi:[1,0]
	v_pk_mul_f32 v[4:5], v[4:5], v[64:65] op_sel_hi:[1,0]
	v_pk_mul_f32 v[6:7], v[6:7], v[64:65] op_sel_hi:[1,0]
	v_pk_mul_f32 v[26:27], v[26:27], v[64:65] op_sel_hi:[1,0]
	v_pk_mul_f32 v[24:25], v[24:25], v[64:65] op_sel_hi:[1,0]
	v_pk_mul_f32 v[8:9], v[8:9], v[64:65] op_sel_hi:[1,0]
	v_pk_mul_f32 v[10:11], v[10:11], v[64:65] op_sel_hi:[1,0]
	s_waitcnt vmcnt(9)
	v_and_b32_e32 v44, 0xffff0000, v38
	v_lshlrev_b32_e32 v45, 16, v39
	v_lshlrev_b32_e32 v38, 16, v38
	v_and_b32_e32 v39, 0xffff0000, v39
	v_pk_add_f32 v[44:45], v[46:47], v[44:45]
	v_pk_add_f32 v[18:19], v[40:41], v[38:39]
	v_and_b32_sdwa v39, v44, v232 dst_sel:DWORD dst_unused:UNUSED_PAD src0_sel:WORD_1 src1_sel:DWORD
	v_and_b32_sdwa v40, v19, v232 dst_sel:DWORD dst_unused:UNUSED_PAD src0_sel:WORD_1 src1_sel:DWORD
	v_and_b32_sdwa v38, v45, v232 dst_sel:DWORD dst_unused:UNUSED_PAD src0_sel:WORD_1 src1_sel:DWORD
	v_add3_u32 v39, v44, v39, s81
	v_and_b32_sdwa v41, v18, v232 dst_sel:DWORD dst_unused:UNUSED_PAD src0_sel:WORD_1 src1_sel:DWORD
	v_add3_u32 v19, v19, v40, s81
	v_add3_u32 v38, v45, v38, s81
	v_and_b32_e32 v39, 0xffff0000, v39
	v_add3_u32 v18, v18, v41, s81
	v_and_b32_e32 v19, 0xffff0000, v19
	v_or_b32_sdwa v19, v19, v38 dst_sel:DWORD dst_unused:UNUSED_PAD src0_sel:DWORD src1_sel:WORD_1
	v_or_b32_sdwa v18, v18, v39 dst_sel:DWORD dst_unused:UNUSED_PAD src0_sel:WORD_1 src1_sel:DWORD
	global_load_dwordx2 v[38:39], v[160:161], off offset:224
	global_load_dwordx2 v[40:41], v[160:161], off offset:240
	v_mov_b32_e32 v47, v2
	v_mov_b32_e32 v2, v1
	v_mov_b32_e32 v46, v0
	v_pk_mul_f32 v[30:31], v[30:31], v[64:65] op_sel_hi:[1,0]
	v_pk_mul_f32 v[28:29], v[28:29], v[64:65] op_sel_hi:[1,0]
	s_waitcnt vmcnt(8)
	v_lshlrev_b32_e32 v45, 16, v37
	v_lshlrev_b32_e32 v44, 16, v36
	v_and_b32_e32 v37, 0xffff0000, v37
	v_and_b32_e32 v36, 0xffff0000, v36
	v_pk_add_f32 v[0:1], v[2:3], v[36:37]
	v_pk_add_f32 v[44:45], v[46:47], v[44:45]
	v_and_b32_sdwa v36, v1, v232 dst_sel:DWORD dst_unused:UNUSED_PAD src0_sel:WORD_1 src1_sel:DWORD
	v_and_b32_sdwa v37, v0, v232 dst_sel:DWORD dst_unused:UNUSED_PAD src0_sel:WORD_1 src1_sel:DWORD
	v_and_b32_sdwa v2, v45, v232 dst_sel:DWORD dst_unused:UNUSED_PAD src0_sel:WORD_1 src1_sel:DWORD
	v_and_b32_sdwa v3, v44, v232 dst_sel:DWORD dst_unused:UNUSED_PAD src0_sel:WORD_1 src1_sel:DWORD
	v_add3_u32 v1, v1, v36, s81
	v_add3_u32 v0, v0, v37, s81
	v_add3_u32 v3, v44, v3, s81
	v_add3_u32 v2, v45, v2, s81
	v_and_b32_e32 v1, 0xffff0000, v1
	v_and_b32_e32 v0, 0xffff0000, v0
	v_or_b32_sdwa v1, v1, v2 dst_sel:DWORD dst_unused:UNUSED_PAD src0_sel:DWORD src1_sel:WORD_1
	v_or_b32_sdwa v0, v0, v3 dst_sel:DWORD dst_unused:UNUSED_PAD src0_sel:DWORD src1_sel:WORD_1
	global_store_dwordx2 v[160:161], v[18:19], off offset:128
	global_store_dwordx2 v[160:161], v[0:1], off offset:192
	v_pk_mov_b32 v[18:19], v[20:21], v[22:23] op_sel:[1,0]
	v_mov_b32_e32 v21, v23
	s_waitcnt vmcnt(9)
	v_and_b32_e32 v0, 0xffff0000, v34
	v_lshlrev_b32_e32 v1, 16, v35
	v_lshlrev_b32_e32 v2, 16, v34
	v_and_b32_e32 v3, 0xffff0000, v35
	v_pk_add_f32 v[0:1], v[18:19], v[0:1]
	v_pk_add_f32 v[2:3], v[20:21], v[2:3]
	v_and_b32_sdwa v18, v1, v232 dst_sel:DWORD dst_unused:UNUSED_PAD src0_sel:WORD_1 src1_sel:DWORD
	v_and_b32_sdwa v19, v0, v232 dst_sel:DWORD dst_unused:UNUSED_PAD src0_sel:WORD_1 src1_sel:DWORD
	v_add3_u32 v1, v1, v18, s81
	v_and_b32_sdwa v18, v3, v232 dst_sel:DWORD dst_unused:UNUSED_PAD src0_sel:WORD_1 src1_sel:DWORD
	v_add3_u32 v0, v0, v19, s81
	v_and_b32_sdwa v19, v2, v232 dst_sel:DWORD dst_unused:UNUSED_PAD src0_sel:WORD_1 src1_sel:DWORD
	v_add3_u32 v3, v3, v18, s81
	v_and_b32_e32 v0, 0xffff0000, v0
	v_add3_u32 v2, v2, v19, s81
	v_and_b32_e32 v3, 0xffff0000, v3
	v_or_b32_sdwa v1, v3, v1 dst_sel:DWORD dst_unused:UNUSED_PAD src0_sel:DWORD src1_sel:WORD_1
	v_or_b32_sdwa v0, v2, v0 dst_sel:DWORD dst_unused:UNUSED_PAD src0_sel:WORD_1 src1_sel:DWORD
	s_waitcnt vmcnt(6)
	v_lshlrev_b32_e32 v3, 16, v33
	v_lshlrev_b32_e32 v2, 16, v32
	v_mov_b32_e32 v20, v4
	v_mov_b32_e32 v21, v6
	v_and_b32_e32 v19, 0xffff0000, v33
	v_and_b32_e32 v18, 0xffff0000, v32
	v_pk_add_f32 v[2:3], v[20:21], v[2:3]
	v_mov_b32_e32 v6, v5
	v_pk_add_f32 v[4:5], v[6:7], v[18:19]
	v_and_b32_sdwa v6, v3, v232 dst_sel:DWORD dst_unused:UNUSED_PAD src0_sel:WORD_1 src1_sel:DWORD
	v_and_b32_sdwa v7, v2, v232 dst_sel:DWORD dst_unused:UNUSED_PAD src0_sel:WORD_1 src1_sel:DWORD
	v_add3_u32 v2, v2, v7, s81
	v_add3_u32 v3, v3, v6, s81
	v_and_b32_sdwa v6, v5, v232 dst_sel:DWORD dst_unused:UNUSED_PAD src0_sel:WORD_1 src1_sel:DWORD
	v_and_b32_sdwa v7, v4, v232 dst_sel:DWORD dst_unused:UNUSED_PAD src0_sel:WORD_1 src1_sel:DWORD
	v_add3_u32 v5, v5, v6, s81
	v_add3_u32 v4, v4, v7, s81
	v_and_b32_e32 v5, 0xffff0000, v5
	v_and_b32_e32 v4, 0xffff0000, v4
	v_or_b32_sdwa v3, v5, v3 dst_sel:DWORD dst_unused:UNUSED_PAD src0_sel:DWORD src1_sel:WORD_1
	v_or_b32_sdwa v2, v4, v2 dst_sel:DWORD dst_unused:UNUSED_PAD src0_sel:DWORD src1_sel:WORD_1
	global_store_dwordx2 v[160:161], v[0:1], off offset:144
	global_store_dwordx2 v[160:161], v[2:3], off offset:208
	s_waitcnt vmcnt(7)
	v_and_b32_e32 v0, 0xffff0000, v14
	v_lshlrev_b32_e32 v1, 16, v15
	v_pk_mov_b32 v[4:5], v[24:25], v[26:27] op_sel:[1,0]
	v_lshlrev_b32_e32 v2, 16, v14
	v_and_b32_e32 v3, 0xffff0000, v15
	v_pk_add_f32 v[0:1], v[4:5], v[0:1]
	v_mov_b32_e32 v25, v27
	v_pk_add_f32 v[2:3], v[24:25], v[2:3]
	v_and_b32_sdwa v4, v1, v232 dst_sel:DWORD dst_unused:UNUSED_PAD src0_sel:WORD_1 src1_sel:DWORD
	v_and_b32_sdwa v5, v0, v232 dst_sel:DWORD dst_unused:UNUSED_PAD src0_sel:WORD_1 src1_sel:DWORD
	v_add3_u32 v1, v1, v4, s81
	v_and_b32_sdwa v4, v3, v232 dst_sel:DWORD dst_unused:UNUSED_PAD src0_sel:WORD_1 src1_sel:DWORD
	v_add3_u32 v0, v0, v5, s81
	v_and_b32_sdwa v5, v2, v232 dst_sel:DWORD dst_unused:UNUSED_PAD src0_sel:WORD_1 src1_sel:DWORD
	v_add3_u32 v3, v3, v4, s81
	v_and_b32_e32 v0, 0xffff0000, v0
	v_add3_u32 v2, v2, v5, s81
	v_and_b32_e32 v3, 0xffff0000, v3
	v_or_b32_sdwa v1, v3, v1 dst_sel:DWORD dst_unused:UNUSED_PAD src0_sel:DWORD src1_sel:WORD_1
	v_or_b32_sdwa v0, v2, v0 dst_sel:DWORD dst_unused:UNUSED_PAD src0_sel:WORD_1 src1_sel:DWORD
	s_waitcnt vmcnt(5)
	v_lshlrev_b32_e32 v3, 16, v39
	v_lshlrev_b32_e32 v2, 16, v38
	v_mov_b32_e32 v6, v8
	v_mov_b32_e32 v7, v10
	v_and_b32_e32 v5, 0xffff0000, v39
	v_and_b32_e32 v4, 0xffff0000, v38
	v_pk_add_f32 v[2:3], v[6:7], v[2:3]
	v_mov_b32_e32 v10, v9
	v_pk_add_f32 v[4:5], v[10:11], v[4:5]
	v_and_b32_sdwa v6, v3, v232 dst_sel:DWORD dst_unused:UNUSED_PAD src0_sel:WORD_1 src1_sel:DWORD
	v_and_b32_sdwa v7, v2, v232 dst_sel:DWORD dst_unused:UNUSED_PAD src0_sel:WORD_1 src1_sel:DWORD
	v_add3_u32 v2, v2, v7, s81
	v_add3_u32 v3, v3, v6, s81
	v_and_b32_sdwa v6, v5, v232 dst_sel:DWORD dst_unused:UNUSED_PAD src0_sel:WORD_1 src1_sel:DWORD
	v_and_b32_sdwa v7, v4, v232 dst_sel:DWORD dst_unused:UNUSED_PAD src0_sel:WORD_1 src1_sel:DWORD
	v_add3_u32 v5, v5, v6, s81
	v_add3_u32 v4, v4, v7, s81
	v_and_b32_e32 v5, 0xffff0000, v5
	v_and_b32_e32 v4, 0xffff0000, v4
	v_or_b32_sdwa v3, v5, v3 dst_sel:DWORD dst_unused:UNUSED_PAD src0_sel:DWORD src1_sel:WORD_1
	v_or_b32_sdwa v2, v4, v2 dst_sel:DWORD dst_unused:UNUSED_PAD src0_sel:DWORD src1_sel:WORD_1
	global_store_dwordx2 v[160:161], v[0:1], off offset:160
	global_store_dwordx2 v[160:161], v[2:3], off offset:224
	v_and_b32_e32 v0, 0xffff0000, v42
	v_lshlrev_b32_e32 v1, 16, v43
	v_pk_mov_b32 v[4:5], v[28:29], v[30:31] op_sel:[1,0]
	v_lshlrev_b32_e32 v2, 16, v42
	v_and_b32_e32 v3, 0xffff0000, v43
	v_pk_add_f32 v[0:1], v[4:5], v[0:1]
	v_mov_b32_e32 v29, v31
	v_pk_add_f32 v[2:3], v[28:29], v[2:3]
	v_and_b32_sdwa v4, v1, v232 dst_sel:DWORD dst_unused:UNUSED_PAD src0_sel:WORD_1 src1_sel:DWORD
	v_and_b32_sdwa v5, v0, v232 dst_sel:DWORD dst_unused:UNUSED_PAD src0_sel:WORD_1 src1_sel:DWORD
	v_add3_u32 v1, v1, v4, s81
	v_and_b32_sdwa v4, v3, v232 dst_sel:DWORD dst_unused:UNUSED_PAD src0_sel:WORD_1 src1_sel:DWORD
	v_add3_u32 v0, v0, v5, s81
	v_and_b32_sdwa v5, v2, v232 dst_sel:DWORD dst_unused:UNUSED_PAD src0_sel:WORD_1 src1_sel:DWORD
	v_add3_u32 v3, v3, v4, s81
	v_and_b32_e32 v0, 0xffff0000, v0
	v_add3_u32 v2, v2, v5, s81
	v_and_b32_e32 v3, 0xffff0000, v3
	v_or_b32_sdwa v1, v3, v1 dst_sel:DWORD dst_unused:UNUSED_PAD src0_sel:DWORD src1_sel:WORD_1
	v_or_b32_sdwa v0, v2, v0 dst_sel:DWORD dst_unused:UNUSED_PAD src0_sel:WORD_1 src1_sel:DWORD
	s_waitcnt vmcnt(6)
	v_lshlrev_b32_e32 v3, 16, v41
	v_lshlrev_b32_e32 v2, 16, v40
	v_mov_b32_e32 v6, v16
	v_mov_b32_e32 v7, v12
	v_and_b32_e32 v5, 0xffff0000, v41
	v_and_b32_e32 v4, 0xffff0000, v40
	v_pk_add_f32 v[2:3], v[6:7], v[2:3]
	v_mov_b32_e32 v12, v17
	v_pk_add_f32 v[4:5], v[12:13], v[4:5]
	v_and_b32_sdwa v6, v3, v232 dst_sel:DWORD dst_unused:UNUSED_PAD src0_sel:WORD_1 src1_sel:DWORD
	v_and_b32_sdwa v7, v2, v232 dst_sel:DWORD dst_unused:UNUSED_PAD src0_sel:WORD_1 src1_sel:DWORD
	v_add3_u32 v2, v2, v7, s81
	v_add3_u32 v3, v3, v6, s81
	v_and_b32_sdwa v6, v5, v232 dst_sel:DWORD dst_unused:UNUSED_PAD src0_sel:WORD_1 src1_sel:DWORD
	v_and_b32_sdwa v7, v4, v232 dst_sel:DWORD dst_unused:UNUSED_PAD src0_sel:WORD_1 src1_sel:DWORD
	v_add3_u32 v5, v5, v6, s81
	v_add3_u32 v4, v4, v7, s81
	v_and_b32_e32 v5, 0xffff0000, v5
	v_and_b32_e32 v4, 0xffff0000, v4
	v_or_b32_sdwa v3, v5, v3 dst_sel:DWORD dst_unused:UNUSED_PAD src0_sel:DWORD src1_sel:WORD_1
	v_or_b32_sdwa v2, v4, v2 dst_sel:DWORD dst_unused:UNUSED_PAD src0_sel:DWORD src1_sel:WORD_1
	global_store_dwordx2 v[160:161], v[0:1], off offset:176
	global_store_dwordx2 v[160:161], v[2:3], off offset:240
	s_nop 0
	s_cbranch_scc1 .LBB0_830
